# attention DMA issue: two straight-line paths by wave half, no per-piece scalar selects
# speedup vs baseline: 1.0265x; 1.0007x over previous
; #define SBAR() __builtin_amdgcn_sched_barrier(0)
; #define WBAR() do { asm volatile("s_waitcnt vmcnt(0) lgkmcnt(0)" ::: "memory"); __builtin_amdgcn_s_barrier(); asm volatile("" ::: "memory"); } while (0)
; #define FIX(a, dlt, P0, P1) do { if (__any((dlt) > 0.f)) { if (hi == 0) al_l[r32] = (a); asm volatile("s_waitcnt lgkmcnt(0)" ::: "memory"); \
;     _Pragma("unroll") for (int d = 0; d < 5; ++d) _Pragma("unroll") for (int r = 0; r < 16; ++r) o[d][r] *= al_l[crow(r, hi)]; \
;     _Pragma("unroll") for (int r = 0; r < 16; ++r) { P0[r] *= (a); P1[r] -= (dlt); negm[r] -= (dlt); } } } while (0)
; __device__ __forceinline__ void attn_unit(const unsigned char* __restrict__ Qb, const unsigned char* __restrict__ Kh, const unsigned char* __restrict__ VTh, f16* __restrict__ Ob, int seq, LAS char* lds) {
;     ...
;         SBAR(); qkt(pB0, pB1, KSL(j), ka0, ka1, qf, negm);
;         finishSM(pA0, pA1, pa); SBAR();
;         pv_d0(o, VSL(j - 1), va0, va1, pa); partialSM<false>(pB0, pB1, negm, dlB, alB);
;         WBAR();
;         { const int J = (j - 1) >> 1; if (J + 2 < NS) ISSUE(J + 2); }
;         FIX(alB, dlB, pB0, pB1);
.LBB0_589:
	s_bitcmp1_b32 s15, 0
	s_cselect_b32 s0, 0x6000, 0
	s_add_i32 s0, s0, 0
	v_add_u32_e32 v0, s0, v244
	v_add_u32_e32 v210, s0, v245
	v_add_u32_e32 v211, 0xf000, v0
	v_add_u32_e32 v212, 0xf000, v210
	ds_read_b128 v[2:5], v0 offset:61504
	ds_read_b128 v[6:9], v210 offset:61504
	v_exp_f32_e32 v14, v116
	v_exp_f32_e32 v15, v117
	v_exp_f32_e32 v12, v114
	v_exp_f32_e32 v13, v115
	s_waitcnt lgkmcnt(4)
	v_mfma_scale_f32_32x32x64_f8f6f4 v[144:159], v[202:209], v[184:191], v[96:111], v234, v233 op_sel_hi:[0,0,0]
	ds_read_b128 v[202:205], v211 offset:6208
	ds_read_b128 v[206:209], v212 offset:6208
	v_exp_f32_e32 v114, v118
	v_exp_f32_e32 v115, v119
	v_exp_f32_e32 v119, v120
	v_exp_f32_e32 v120, v121
	v_cvt_pk_fp8_f32 v117, v14, v15
	v_exp_f32_e32 v10, v112
	v_exp_f32_e32 v11, v113
	s_waitcnt lgkmcnt(4)
	v_mfma_scale_f32_32x32x64_f8f6f4 v[128:143], v[194:201], v[184:191], v[96:111], v234, v233 op_sel_hi:[0,0,0]
	ds_read_b128 v[194:197], v0 offset:61568
	ds_read_b128 v[198:201], v210 offset:61568
	v_exp_f32_e32 v121, v122
	v_exp_f32_e32 v122, v123
	v_exp_f32_e32 v123, v124
	v_exp_f32_e32 v124, v125
	v_cvt_pk_fp8_f32 v117, v114, v115 op_sel:[0,0,1]
	v_cvt_pk_fp8_f32 v118, v119, v120
	v_exp_f32_e32 v125, v126
	s_waitcnt lgkmcnt(4)
	v_mfma_scale_f32_32x32x64_f8f6f4 v[144:159], v[2:9], v[176:183], v[144:159], v234, v233 op_sel_hi:[0,0,0]
	ds_read_b128 v[2:5], v211 offset:6272
	ds_read_b128 v[6:9], v212 offset:6272
	v_exp_f32_e32 v126, v127
	v_cvt_pk_fp8_f32 v112, v228, v229
	v_cvt_pk_fp8_f32 v116, v10, v11
	v_cvt_pk_fp8_f32 v113, v226, v227
	v_cvt_pk_fp8_f32 v114, v222, v223
	v_cvt_pk_fp8_f32 v115, v166, v167
	s_waitcnt lgkmcnt(4)
	v_mfma_scale_f32_32x32x64_f8f6f4 v[128:143], v[202:209], v[176:183], v[128:143], v234, v233 op_sel_hi:[0,0,0]
	v_cvt_pk_fp8_f32 v119, v123, v124
	v_cvt_pk_fp8_f32 v112, v220, v221 op_sel:[0,0,1]
	v_cvt_pk_fp8_f32 v116, v12, v13 op_sel:[0,0,1]
	v_cvt_pk_fp8_f32 v113, v224, v225 op_sel:[0,0,1]
	v_cvt_pk_fp8_f32 v114, v162, v163 op_sel:[0,0,1]
	v_cvt_pk_fp8_f32 v118, v121, v122 op_sel:[0,0,1]
	s_waitcnt lgkmcnt(2)
	v_mfma_scale_f32_32x32x64_f8f6f4 v[144:159], v[194:201], v[168:175], v[144:159], v234, v233 op_sel_hi:[0,0,0]
	v_cvt_pk_fp8_f32 v115, v164, v165 op_sel:[0,0,1]
	v_cvt_pk_fp8_f32 v119, v125, v126 op_sel:[0,0,1]
	v_mov_b32_e32 v161, v160
	v_mov_b32_e32 v162, v160
	v_mov_b32_e32 v163, v160
	s_waitcnt lgkmcnt(0)
	v_mfma_scale_f32_32x32x64_f8f6f4 v[128:143], v[2:9], v[168:175], v[128:143], v234, v233 op_sel_hi:[0,0,0]
	v_mov_b32_e32 v164, v160
	v_mov_b32_e32 v165, v160
	v_mov_b32_e32 v166, v160
	v_mov_b32_e32 v167, v160
	s_add_i32 s66, s21, -2
	s_ashr_i32 s38, s66, 1
	s_mul_hi_i32 s0, s38, 0x55555556
	s_lshr_b32 s1, s0, 31
	s_add_i32 s0, s0, s1
	s_mul_i32 s0, s0, 3
	s_sub_i32 s0, s38, s0
	s_lshl_b32 s0, s0, 14
	s_add_i32 s0, s0, 0
	v_add_u32_e32 v0, s0, v241
	v_add_u32_e32 v11, s0, v240
	ds_read_b128 v[208:211], v0
	ds_read_b128 v[212:215], v11
	ds_read_b128 v[200:203], v0 offset:2048
	ds_read_b128 v[204:207], v11 offset:2048
	ds_read_b128 v[192:195], v0 offset:4096
	ds_read_b128 v[196:199], v11 offset:4096
	ds_read_b128 v[2:5], v0 offset:6144
	ds_read_b128 v[6:9], v11 offset:6144
	v_mov_b32_e32 v125, 0x19000
	v_lshl_add_u32 v126, v216, 4, v125
	v_lshl_add_u32 v127, v216, 2, v125
	ds_read_b128 v[120:123], v126
	ds_read_b32 v124, v127 offset:8192
	v_max_f32_e32 v0, v144, v145
	v_max3_f32 v0, v0, v146, v147
	v_max3_f32 v0, v0, v148, v149
	v_max3_f32 v0, v0, v150, v151
	v_max3_f32 v0, v0, v152, v153
	v_max3_f32 v0, v0, v154, v155
	v_max3_f32 v0, v0, v156, v157
	v_max3_f32 v0, v0, v158, v159
	s_waitcnt lgkmcnt(8)
	v_mfma_scale_f32_32x32x64_f8f6f4 v[64:79], v[112:119], v[208:215], v[64:79], v234, v234 op_sel_hi:[0,0,0]
	v_exp_f32_e32 v14, v144
	v_exp_f32_e32 v15, v145
	v_exp_f32_e32 v10, v148
	v_exp_f32_e32 v11, v149
	v_max3_f32 v0, v0, v128, v129
	v_max3_f32 v0, v0, v130, v131
	v_max3_f32 v0, v0, v132, v133
	v_max3_f32 v0, v0, v134, v135
	s_waitcnt lgkmcnt(6)
	v_mfma_scale_f32_32x32x64_f8f6f4 v[48:63], v[112:119], v[200:207], v[48:63], v234, v234 op_sel_hi:[0,0,0]
	v_exp_f32_e32 v12, v150
	v_exp_f32_e32 v13, v151
	v_max3_f32 v0, v0, v136, v137
	v_max3_f32 v0, v0, v138, v139
	v_max3_f32 v0, v0, v140, v141
	v_max3_f32 v0, v0, v142, v143
	s_waitcnt lgkmcnt(4)
	v_mfma_scale_f32_32x32x64_f8f6f4 v[32:47], v[112:119], v[192:199], v[32:47], v234, v234 op_sel_hi:[0,0,0]
	v_exp_f32_e32 v192, v146
	v_exp_f32_e32 v193, v147
	v_mov_b32_e32 v125, v0
	s_nop 1
	v_permlane32_swap_b32_e32 v0, v125
	s_waitcnt lgkmcnt(2)
	v_mfma_scale_f32_32x32x64_f8f6f4 v[16:31], v[112:119], v[2:9], v[16:31], v234, v234 op_sel_hi:[0,0,0]
	v_exp_f32_e32 v6, v152
	v_exp_f32_e32 v7, v153
	v_exp_f32_e32 v8, v154
	v_exp_f32_e32 v9, v155
	v_exp_f32_e32 v2, v156
	v_exp_f32_e32 v3, v157
	v_exp_f32_e32 v4, v158
	v_exp_f32_e32 v5, v159
	v_mfma_scale_f32_32x32x64_f8f6f4 v[80:95], v[112:119], v[160:167], v[80:95], v234, v234 op_sel_hi:[0,0,0]
	s_waitcnt vmcnt(0) lgkmcnt(0)
	s_barrier
	v_max_f32_e32 v0, v0, v125
	s_add_i32 s42, s38, 2
	v_cmp_ge_f32_e64 s[0:1], s67, v0
	s_cmp_ge_i32 s42, s14
	s_cbranch_scc1 .Lattn_noissue
	s_bitcmp1_b32 s21, 1
	s_cselect_b32 s44, 0x6000, 0
	v_add_u32_e32 v126, s44, v244
	v_add_u32_e32 v127, s44, v245
	ds_read_b128 v[208:211], v126 offset:49152
	ds_read_b128 v[212:215], v127 offset:49152
	s_ashr_i32 s43, s42, 31
	s_mul_i32 s38, s42, 0x18000
	s_mul_hi_i32 s39, s42, 0x18000
	s_add_u32 s38, s24, s38
	s_addc_u32 s39, s25, s39
	s_lshl_b64 s[40:41], s[42:43], 14
	s_add_u32 s40, s52, s40
	s_addc_u32 s41, s53, s41
	s_mul_hi_i32 s43, s42, 0x55555556
	s_lshr_b32 s67, s43, 31
	s_add_i32 s43, s43, s67
	s_mul_i32 s43, s43, 3
	s_sub_i32 s42, s42, s43
	s_lshl_b32 s67, s42, 14
	s_bitcmp1_b32 s66, 1
	s_mov_b32 s42, 0xa000
	s_cselect_b32 s66, 0x10000, s42
	s_and_b64 vcc, exec, s[6:7]
	s_cbranch_vccnz .Lattn_iss_hi
	s_add_i32 m0, s67, s28
	s_nop 0
	global_load_lds_dwordx4 v120, s[40:41]
	s_add_i32 m0, s2, s66
	s_nop 0
	global_load_lds_dwordx4 v121, s[38:39]
	s_add_i32 m0, s27, s66
	s_nop 0
	global_load_lds_dwordx4 v122, s[38:39]
	s_add_i32 m0, s67, s31
	s_nop 0
	global_load_lds_dwordx4 v123, s[40:41]
	s_add_i32 m0, s33, s66
	s_nop 0
	global_load_lds_dwordx4 v124, s[38:39]
	s_branch .Lattn_iss_done
.Lattn_iss_hi:
	s_add_i32 m0, s67, s28
	s_nop 0
	global_load_lds_dwordx4 v120, s[40:41]
	s_add_i32 m0, s2, s66
	s_nop 0
	global_load_lds_dwordx4 v121, s[38:39]
	s_add_i32 m0, s67, s26
	s_nop 0
	global_load_lds_dwordx4 v122, s[40:41]
	s_add_i32 m0, s49, s66
	s_nop 0
	global_load_lds_dwordx4 v123, s[38:39]
	s_add_i32 m0, s33, s66
	s_nop 0
	global_load_lds_dwordx4 v124, s[38:39]
.Lattn_iss_done:
	s_mov_b32 s67, 0x41000000
	ds_read_b128 v[120:123], v126 offset:55296
	ds_read_b128 v[124:127], v127 offset:55296
	s_cmp_lg_u64 s[0:1], exec
	s_cbranch_scc0 .LBB0_615
	s_branch .Lattn_fix1
